# packed inversion + packed d16_hi output stores + deferred beta/decay copy
# baseline (speedup 1.0000x reference)
.LBB0_664:
	s_or_saveexec_b64 s[12:13], s[16:17]
	v_and_b32_e32 v95, 31, v94
	s_xor_b64 exec, exec, s[12:13]
	s_cbranch_execz .LBB0_666
	v_and_b32_e32 v0, 32, v94
	v_lshlrev_b32_e32 v1, 8, v0
	v_lshlrev_b32_e32 v2, 2, v0
	v_add3_u32 v11, s91, v1, v2
	v_mov_b32_e32 v241, 0
	v_mov_b32_e32 v249, 0
	ds_read_b128 v[204:207], v11 offset:256
	v_cmp_eq_u32_e32 vcc, 0, v95
	v_lshl_add_u32 v244, v95, 1, s95
	v_mad_u32_u24 v0, v0, s93, v244
	v_cndmask_b32_e64 v12, 0, 1.0, vcc
	v_cmp_eq_u32_e32 vcc, 1, v95
	s_nop 1
	v_cndmask_b32_e64 v248, 0, 1.0, vcc
	v_cmp_eq_u32_e32 vcc, 2, v95
	ds_read_b128 v[172:175], v11 offset:512
	s_waitcnt lgkmcnt(1)
	v_cndmask_b32_e64 v240, 0, 1.0, vcc
	v_fma_f32 v13, -v204, v12, v248
	v_cmp_eq_u32_e32 vcc, 3, v95
	ds_read_b128 v[204:207], v11 offset:768
	s_waitcnt lgkmcnt(1)
	v_pk_fma_f32 v[242:243], v[172:173], v[12:13], v[240:241] neg_lo:[1,0,0] neg_hi:[1,0,0]
	v_cndmask_b32_e64 v248, 0, 1.0, vcc
	v_add_f32_e32 v14, v242, v243
	v_cmp_eq_u32_e32 vcc, 4, v95
	ds_read_b128 v[172:175], v11 offset:1024
	s_waitcnt lgkmcnt(1)
	v_pk_fma_f32 v[242:243], v[204:205], v[12:13], v[248:249] neg_lo:[1,0,0] neg_hi:[1,0,0]
	v_cndmask_b32_e64 v240, 0, 1.0, vcc
	v_fma_f32 v242, -v206, v14, v242
	v_add_f32_e32 v15, v242, v243
	v_cmp_eq_u32_e32 vcc, 5, v95
	ds_read_b128 v[204:207], v11 offset:1280
	ds_read_b128 v[208:211], v11 offset:1296
	s_waitcnt lgkmcnt(2)
	v_pk_fma_f32 v[242:243], v[172:173], v[12:13], v[240:241] neg_lo:[1,0,0] neg_hi:[1,0,0]
	v_pk_fma_f32 v[242:243], v[174:175], v[14:15], v[242:243] neg_lo:[1,0,0] neg_hi:[1,0,0]
	v_cndmask_b32_e64 v248, 0, 1.0, vcc
	v_add_f32_e32 v16, v242, v243
	v_cmp_eq_u32_e32 vcc, 6, v95
	ds_read_b128 v[172:175], v11 offset:1536
	ds_read_b128 v[176:179], v11 offset:1552
	s_waitcnt lgkmcnt(2)
	v_pk_fma_f32 v[242:243], v[204:205], v[12:13], v[248:249] neg_lo:[1,0,0] neg_hi:[1,0,0]
	v_pk_fma_f32 v[242:243], v[206:207], v[14:15], v[242:243] neg_lo:[1,0,0] neg_hi:[1,0,0]
	v_cndmask_b32_e64 v240, 0, 1.0, vcc
	v_fma_f32 v242, -v208, v16, v242
	v_add_f32_e32 v17, v242, v243
	v_cmp_eq_u32_e32 vcc, 7, v95
	ds_read_b128 v[204:207], v11 offset:1792
	ds_read_b128 v[208:211], v11 offset:1808
	s_waitcnt lgkmcnt(2)
	v_pk_fma_f32 v[242:243], v[172:173], v[12:13], v[240:241] neg_lo:[1,0,0] neg_hi:[1,0,0]
	v_pk_fma_f32 v[242:243], v[174:175], v[14:15], v[242:243] neg_lo:[1,0,0] neg_hi:[1,0,0]
	v_pk_fma_f32 v[242:243], v[176:177], v[16:17], v[242:243] neg_lo:[1,0,0] neg_hi:[1,0,0]
	v_cndmask_b32_e64 v248, 0, 1.0, vcc
	v_add_f32_e32 v18, v242, v243
	v_cmp_eq_u32_e32 vcc, 8, v95
	ds_read_b128 v[172:175], v11 offset:2048
	ds_read_b128 v[176:179], v11 offset:2064
	s_waitcnt lgkmcnt(2)
	v_pk_fma_f32 v[242:243], v[204:205], v[12:13], v[248:249] neg_lo:[1,0,0] neg_hi:[1,0,0]
	v_pk_fma_f32 v[242:243], v[206:207], v[14:15], v[242:243] neg_lo:[1,0,0] neg_hi:[1,0,0]
	v_pk_fma_f32 v[242:243], v[208:209], v[16:17], v[242:243] neg_lo:[1,0,0] neg_hi:[1,0,0]
	v_cndmask_b32_e64 v240, 0, 1.0, vcc
	v_fma_f32 v242, -v210, v18, v242
	v_add_f32_e32 v19, v242, v243
	v_cmp_eq_u32_e32 vcc, 9, v95
	ds_read_b128 v[204:207], v11 offset:2304
	ds_read_b128 v[208:211], v11 offset:2320
	ds_read_b128 v[212:215], v11 offset:2336
	s_waitcnt lgkmcnt(3)
	v_pk_fma_f32 v[242:243], v[172:173], v[12:13], v[240:241] neg_lo:[1,0,0] neg_hi:[1,0,0]
	v_pk_fma_f32 v[242:243], v[174:175], v[14:15], v[242:243] neg_lo:[1,0,0] neg_hi:[1,0,0]
	v_pk_fma_f32 v[242:243], v[176:177], v[16:17], v[242:243] neg_lo:[1,0,0] neg_hi:[1,0,0]
	v_pk_fma_f32 v[242:243], v[178:179], v[18:19], v[242:243] neg_lo:[1,0,0] neg_hi:[1,0,0]
	v_cndmask_b32_e64 v248, 0, 1.0, vcc
	v_add_f32_e32 v20, v242, v243
	v_cmp_eq_u32_e32 vcc, 10, v95
	ds_read_b128 v[172:175], v11 offset:2560
	ds_read_b128 v[176:179], v11 offset:2576
	ds_read_b128 v[180:183], v11 offset:2592
	s_waitcnt lgkmcnt(3)
	v_pk_fma_f32 v[242:243], v[204:205], v[12:13], v[248:249] neg_lo:[1,0,0] neg_hi:[1,0,0]
	v_pk_fma_f32 v[242:243], v[206:207], v[14:15], v[242:243] neg_lo:[1,0,0] neg_hi:[1,0,0]
	v_pk_fma_f32 v[242:243], v[208:209], v[16:17], v[242:243] neg_lo:[1,0,0] neg_hi:[1,0,0]
	v_pk_fma_f32 v[242:243], v[210:211], v[18:19], v[242:243] neg_lo:[1,0,0] neg_hi:[1,0,0]
	v_cndmask_b32_e64 v240, 0, 1.0, vcc
	v_fma_f32 v242, -v212, v20, v242
	v_add_f32_e32 v21, v242, v243
	v_cmp_eq_u32_e32 vcc, 11, v95
	ds_read_b128 v[204:207], v11 offset:2816
	ds_read_b128 v[208:211], v11 offset:2832
	ds_read_b128 v[212:215], v11 offset:2848
	s_waitcnt lgkmcnt(3)
	v_pk_fma_f32 v[242:243], v[172:173], v[12:13], v[240:241] neg_lo:[1,0,0] neg_hi:[1,0,0]
	v_pk_fma_f32 v[242:243], v[174:175], v[14:15], v[242:243] neg_lo:[1,0,0] neg_hi:[1,0,0]
	v_pk_fma_f32 v[242:243], v[176:177], v[16:17], v[242:243] neg_lo:[1,0,0] neg_hi:[1,0,0]
	v_pk_fma_f32 v[242:243], v[178:179], v[18:19], v[242:243] neg_lo:[1,0,0] neg_hi:[1,0,0]
	v_pk_fma_f32 v[242:243], v[180:181], v[20:21], v[242:243] neg_lo:[1,0,0] neg_hi:[1,0,0]
	v_cndmask_b32_e64 v248, 0, 1.0, vcc
	v_add_f32_e32 v22, v242, v243
	v_cmp_eq_u32_e32 vcc, 12, v95
	ds_read_b128 v[172:175], v11 offset:3072
	ds_read_b128 v[176:179], v11 offset:3088
	ds_read_b128 v[180:183], v11 offset:3104
	s_waitcnt lgkmcnt(3)
	v_pk_fma_f32 v[242:243], v[204:205], v[12:13], v[248:249] neg_lo:[1,0,0] neg_hi:[1,0,0]
	v_pk_fma_f32 v[242:243], v[206:207], v[14:15], v[242:243] neg_lo:[1,0,0] neg_hi:[1,0,0]
	v_pk_fma_f32 v[242:243], v[208:209], v[16:17], v[242:243] neg_lo:[1,0,0] neg_hi:[1,0,0]
	v_pk_fma_f32 v[242:243], v[210:211], v[18:19], v[242:243] neg_lo:[1,0,0] neg_hi:[1,0,0]
	v_pk_fma_f32 v[242:243], v[212:213], v[20:21], v[242:243] neg_lo:[1,0,0] neg_hi:[1,0,0]
	v_cndmask_b32_e64 v240, 0, 1.0, vcc
	v_fma_f32 v242, -v214, v22, v242
	v_add_f32_e32 v23, v242, v243
	v_cmp_eq_u32_e32 vcc, 13, v95
	ds_read_b128 v[204:207], v11 offset:3328
	ds_read_b128 v[208:211], v11 offset:3344
	ds_read_b128 v[212:215], v11 offset:3360
	ds_read_b128 v[216:219], v11 offset:3376
	s_waitcnt lgkmcnt(4)
	v_pk_fma_f32 v[242:243], v[172:173], v[12:13], v[240:241] neg_lo:[1,0,0] neg_hi:[1,0,0]
	v_pk_fma_f32 v[242:243], v[174:175], v[14:15], v[242:243] neg_lo:[1,0,0] neg_hi:[1,0,0]
	v_pk_fma_f32 v[242:243], v[176:177], v[16:17], v[242:243] neg_lo:[1,0,0] neg_hi:[1,0,0]
	v_pk_fma_f32 v[242:243], v[178:179], v[18:19], v[242:243] neg_lo:[1,0,0] neg_hi:[1,0,0]
	v_pk_fma_f32 v[242:243], v[180:181], v[20:21], v[242:243] neg_lo:[1,0,0] neg_hi:[1,0,0]
	v_pk_fma_f32 v[242:243], v[182:183], v[22:23], v[242:243] neg_lo:[1,0,0] neg_hi:[1,0,0]
	v_cndmask_b32_e64 v248, 0, 1.0, vcc
	v_add_f32_e32 v24, v242, v243
	v_cmp_eq_u32_e32 vcc, 14, v95
	ds_read_b128 v[172:175], v11 offset:3584
	ds_read_b128 v[176:179], v11 offset:3600
	ds_read_b128 v[180:183], v11 offset:3616
	ds_read_b128 v[184:187], v11 offset:3632
	s_waitcnt lgkmcnt(4)
	v_pk_fma_f32 v[242:243], v[204:205], v[12:13], v[248:249] neg_lo:[1,0,0] neg_hi:[1,0,0]
	v_pk_fma_f32 v[242:243], v[206:207], v[14:15], v[242:243] neg_lo:[1,0,0] neg_hi:[1,0,0]
	v_pk_fma_f32 v[242:243], v[208:209], v[16:17], v[242:243] neg_lo:[1,0,0] neg_hi:[1,0,0]
	v_pk_fma_f32 v[242:243], v[210:211], v[18:19], v[242:243] neg_lo:[1,0,0] neg_hi:[1,0,0]
	v_pk_fma_f32 v[242:243], v[212:213], v[20:21], v[242:243] neg_lo:[1,0,0] neg_hi:[1,0,0]
	v_pk_fma_f32 v[242:243], v[214:215], v[22:23], v[242:243] neg_lo:[1,0,0] neg_hi:[1,0,0]
	v_cndmask_b32_e64 v240, 0, 1.0, vcc
	v_fma_f32 v242, -v216, v24, v242
	v_add_f32_e32 v25, v242, v243
	v_cmp_eq_u32_e32 vcc, 15, v95
	ds_read_b128 v[204:207], v11 offset:3840
	ds_read_b128 v[208:211], v11 offset:3856
	ds_read_b128 v[212:215], v11 offset:3872
	ds_read_b128 v[216:219], v11 offset:3888
	s_waitcnt lgkmcnt(4)
	v_pk_fma_f32 v[242:243], v[172:173], v[12:13], v[240:241] neg_lo:[1,0,0] neg_hi:[1,0,0]
	v_pk_fma_f32 v[242:243], v[174:175], v[14:15], v[242:243] neg_lo:[1,0,0] neg_hi:[1,0,0]
	v_pk_fma_f32 v[242:243], v[176:177], v[16:17], v[242:243] neg_lo:[1,0,0] neg_hi:[1,0,0]
	v_pk_fma_f32 v[242:243], v[178:179], v[18:19], v[242:243] neg_lo:[1,0,0] neg_hi:[1,0,0]
	v_pk_fma_f32 v[242:243], v[180:181], v[20:21], v[242:243] neg_lo:[1,0,0] neg_hi:[1,0,0]
	v_pk_fma_f32 v[242:243], v[182:183], v[22:23], v[242:243] neg_lo:[1,0,0] neg_hi:[1,0,0]
	v_pk_fma_f32 v[242:243], v[184:185], v[24:25], v[242:243] neg_lo:[1,0,0] neg_hi:[1,0,0]
	v_cndmask_b32_e64 v248, 0, 1.0, vcc
	v_add_f32_e32 v26, v242, v243
	v_cmp_eq_u32_e32 vcc, 16, v95
	ds_read_b128 v[172:175], v11 offset:4096
	ds_read_b128 v[176:179], v11 offset:4112
	ds_read_b128 v[180:183], v11 offset:4128
	ds_read_b128 v[184:187], v11 offset:4144
	s_waitcnt lgkmcnt(4)
	v_pk_fma_f32 v[242:243], v[204:205], v[12:13], v[248:249] neg_lo:[1,0,0] neg_hi:[1,0,0]
	v_pk_fma_f32 v[242:243], v[206:207], v[14:15], v[242:243] neg_lo:[1,0,0] neg_hi:[1,0,0]
	v_pk_fma_f32 v[242:243], v[208:209], v[16:17], v[242:243] neg_lo:[1,0,0] neg_hi:[1,0,0]
	v_pk_fma_f32 v[242:243], v[210:211], v[18:19], v[242:243] neg_lo:[1,0,0] neg_hi:[1,0,0]
	v_pk_fma_f32 v[242:243], v[212:213], v[20:21], v[242:243] neg_lo:[1,0,0] neg_hi:[1,0,0]
	v_pk_fma_f32 v[242:243], v[214:215], v[22:23], v[242:243] neg_lo:[1,0,0] neg_hi:[1,0,0]
	v_pk_fma_f32 v[242:243], v[216:217], v[24:25], v[242:243] neg_lo:[1,0,0] neg_hi:[1,0,0]
	v_cndmask_b32_e64 v240, 0, 1.0, vcc
	v_fma_f32 v242, -v218, v26, v242
	v_add_f32_e32 v27, v242, v243
	v_cmp_eq_u32_e32 vcc, 17, v95
	ds_read_b128 v[204:207], v11 offset:4352
	ds_read_b128 v[208:211], v11 offset:4368
	ds_read_b128 v[212:215], v11 offset:4384
	ds_read_b128 v[216:219], v11 offset:4400
	ds_read_b128 v[220:223], v11 offset:4416
	s_waitcnt lgkmcnt(5)
	v_pk_fma_f32 v[242:243], v[172:173], v[12:13], v[240:241] neg_lo:[1,0,0] neg_hi:[1,0,0]
	v_pk_fma_f32 v[242:243], v[174:175], v[14:15], v[242:243] neg_lo:[1,0,0] neg_hi:[1,0,0]
	v_pk_fma_f32 v[242:243], v[176:177], v[16:17], v[242:243] neg_lo:[1,0,0] neg_hi:[1,0,0]
	v_pk_fma_f32 v[242:243], v[178:179], v[18:19], v[242:243] neg_lo:[1,0,0] neg_hi:[1,0,0]
	v_pk_fma_f32 v[242:243], v[180:181], v[20:21], v[242:243] neg_lo:[1,0,0] neg_hi:[1,0,0]
	v_pk_fma_f32 v[242:243], v[182:183], v[22:23], v[242:243] neg_lo:[1,0,0] neg_hi:[1,0,0]
	v_pk_fma_f32 v[242:243], v[184:185], v[24:25], v[242:243] neg_lo:[1,0,0] neg_hi:[1,0,0]
	v_pk_fma_f32 v[242:243], v[186:187], v[26:27], v[242:243] neg_lo:[1,0,0] neg_hi:[1,0,0]
	v_cndmask_b32_e64 v248, 0, 1.0, vcc
	v_add_f32_e32 v28, v242, v243
	v_cmp_eq_u32_e32 vcc, 18, v95
	ds_read_b128 v[172:175], v11 offset:4608
	ds_read_b128 v[176:179], v11 offset:4624
	ds_read_b128 v[180:183], v11 offset:4640
	ds_read_b128 v[184:187], v11 offset:4656
	ds_read_b128 v[188:191], v11 offset:4672
	s_waitcnt lgkmcnt(5)
	v_pk_fma_f32 v[242:243], v[204:205], v[12:13], v[248:249] neg_lo:[1,0,0] neg_hi:[1,0,0]
	v_pk_fma_f32 v[242:243], v[206:207], v[14:15], v[242:243] neg_lo:[1,0,0] neg_hi:[1,0,0]
	v_pk_fma_f32 v[242:243], v[208:209], v[16:17], v[242:243] neg_lo:[1,0,0] neg_hi:[1,0,0]
	v_pk_fma_f32 v[242:243], v[210:211], v[18:19], v[242:243] neg_lo:[1,0,0] neg_hi:[1,0,0]
	v_pk_fma_f32 v[242:243], v[212:213], v[20:21], v[242:243] neg_lo:[1,0,0] neg_hi:[1,0,0]
	v_pk_fma_f32 v[242:243], v[214:215], v[22:23], v[242:243] neg_lo:[1,0,0] neg_hi:[1,0,0]
	v_pk_fma_f32 v[242:243], v[216:217], v[24:25], v[242:243] neg_lo:[1,0,0] neg_hi:[1,0,0]
	v_pk_fma_f32 v[242:243], v[218:219], v[26:27], v[242:243] neg_lo:[1,0,0] neg_hi:[1,0,0]
	v_cndmask_b32_e64 v240, 0, 1.0, vcc
	v_fma_f32 v242, -v220, v28, v242
	v_add_f32_e32 v29, v242, v243
	v_cmp_eq_u32_e32 vcc, 19, v95
	ds_read_b128 v[204:207], v11 offset:4864
	ds_read_b128 v[208:211], v11 offset:4880
	ds_read_b128 v[212:215], v11 offset:4896
	ds_read_b128 v[216:219], v11 offset:4912
	ds_read_b128 v[220:223], v11 offset:4928
	s_waitcnt lgkmcnt(5)
	v_pk_fma_f32 v[242:243], v[172:173], v[12:13], v[240:241] neg_lo:[1,0,0] neg_hi:[1,0,0]
	v_pk_fma_f32 v[242:243], v[174:175], v[14:15], v[242:243] neg_lo:[1,0,0] neg_hi:[1,0,0]
	v_pk_fma_f32 v[242:243], v[176:177], v[16:17], v[242:243] neg_lo:[1,0,0] neg_hi:[1,0,0]
	v_pk_fma_f32 v[242:243], v[178:179], v[18:19], v[242:243] neg_lo:[1,0,0] neg_hi:[1,0,0]
	v_pk_fma_f32 v[242:243], v[180:181], v[20:21], v[242:243] neg_lo:[1,0,0] neg_hi:[1,0,0]
	v_pk_fma_f32 v[242:243], v[182:183], v[22:23], v[242:243] neg_lo:[1,0,0] neg_hi:[1,0,0]
	v_pk_fma_f32 v[242:243], v[184:185], v[24:25], v[242:243] neg_lo:[1,0,0] neg_hi:[1,0,0]
	v_pk_fma_f32 v[242:243], v[186:187], v[26:27], v[242:243] neg_lo:[1,0,0] neg_hi:[1,0,0]
	v_pk_fma_f32 v[242:243], v[188:189], v[28:29], v[242:243] neg_lo:[1,0,0] neg_hi:[1,0,0]
	v_cndmask_b32_e64 v248, 0, 1.0, vcc
	v_add_f32_e32 v30, v242, v243
	v_cmp_eq_u32_e32 vcc, 20, v95
	ds_read_b128 v[172:175], v11 offset:5120
	ds_read_b128 v[176:179], v11 offset:5136
	ds_read_b128 v[180:183], v11 offset:5152
	ds_read_b128 v[184:187], v11 offset:5168
	ds_read_b128 v[188:191], v11 offset:5184
	s_waitcnt lgkmcnt(5)
	v_pk_fma_f32 v[242:243], v[204:205], v[12:13], v[248:249] neg_lo:[1,0,0] neg_hi:[1,0,0]
	v_pk_fma_f32 v[242:243], v[206:207], v[14:15], v[242:243] neg_lo:[1,0,0] neg_hi:[1,0,0]
	v_pk_fma_f32 v[242:243], v[208:209], v[16:17], v[242:243] neg_lo:[1,0,0] neg_hi:[1,0,0]
	v_pk_fma_f32 v[242:243], v[210:211], v[18:19], v[242:243] neg_lo:[1,0,0] neg_hi:[1,0,0]
	v_pk_fma_f32 v[242:243], v[212:213], v[20:21], v[242:243] neg_lo:[1,0,0] neg_hi:[1,0,0]
	v_pk_fma_f32 v[242:243], v[214:215], v[22:23], v[242:243] neg_lo:[1,0,0] neg_hi:[1,0,0]
	v_pk_fma_f32 v[242:243], v[216:217], v[24:25], v[242:243] neg_lo:[1,0,0] neg_hi:[1,0,0]
	v_pk_fma_f32 v[242:243], v[218:219], v[26:27], v[242:243] neg_lo:[1,0,0] neg_hi:[1,0,0]
	v_pk_fma_f32 v[242:243], v[220:221], v[28:29], v[242:243] neg_lo:[1,0,0] neg_hi:[1,0,0]
	v_cndmask_b32_e64 v240, 0, 1.0, vcc
	v_fma_f32 v242, -v222, v30, v242
	v_add_f32_e32 v31, v242, v243
	v_cmp_eq_u32_e32 vcc, 21, v95
	ds_read_b128 v[204:207], v11 offset:5376
	ds_read_b128 v[208:211], v11 offset:5392
	ds_read_b128 v[212:215], v11 offset:5408
	ds_read_b128 v[216:219], v11 offset:5424
	ds_read_b128 v[220:223], v11 offset:5440
	ds_read_b128 v[224:227], v11 offset:5456
	s_waitcnt lgkmcnt(6)
	v_pk_fma_f32 v[242:243], v[172:173], v[12:13], v[240:241] neg_lo:[1,0,0] neg_hi:[1,0,0]
	v_pk_fma_f32 v[242:243], v[174:175], v[14:15], v[242:243] neg_lo:[1,0,0] neg_hi:[1,0,0]
	v_pk_fma_f32 v[242:243], v[176:177], v[16:17], v[242:243] neg_lo:[1,0,0] neg_hi:[1,0,0]
	v_pk_fma_f32 v[242:243], v[178:179], v[18:19], v[242:243] neg_lo:[1,0,0] neg_hi:[1,0,0]
	v_pk_fma_f32 v[242:243], v[180:181], v[20:21], v[242:243] neg_lo:[1,0,0] neg_hi:[1,0,0]
	v_pk_fma_f32 v[242:243], v[182:183], v[22:23], v[242:243] neg_lo:[1,0,0] neg_hi:[1,0,0]
	v_pk_fma_f32 v[242:243], v[184:185], v[24:25], v[242:243] neg_lo:[1,0,0] neg_hi:[1,0,0]
	v_pk_fma_f32 v[242:243], v[186:187], v[26:27], v[242:243] neg_lo:[1,0,0] neg_hi:[1,0,0]
	v_pk_fma_f32 v[242:243], v[188:189], v[28:29], v[242:243] neg_lo:[1,0,0] neg_hi:[1,0,0]
	v_pk_fma_f32 v[242:243], v[190:191], v[30:31], v[242:243] neg_lo:[1,0,0] neg_hi:[1,0,0]
	v_cndmask_b32_e64 v248, 0, 1.0, vcc
	v_add_f32_e32 v32, v242, v243
	v_cmp_eq_u32_e32 vcc, 22, v95
	ds_read_b128 v[172:175], v11 offset:5632
	ds_read_b128 v[176:179], v11 offset:5648
	ds_read_b128 v[180:183], v11 offset:5664
	ds_read_b128 v[184:187], v11 offset:5680
	ds_read_b128 v[188:191], v11 offset:5696
	ds_read_b128 v[192:195], v11 offset:5712
	s_waitcnt lgkmcnt(6)
	v_pk_fma_f32 v[242:243], v[204:205], v[12:13], v[248:249] neg_lo:[1,0,0] neg_hi:[1,0,0]
	v_pk_fma_f32 v[242:243], v[206:207], v[14:15], v[242:243] neg_lo:[1,0,0] neg_hi:[1,0,0]
	v_pk_fma_f32 v[242:243], v[208:209], v[16:17], v[242:243] neg_lo:[1,0,0] neg_hi:[1,0,0]
	v_pk_fma_f32 v[242:243], v[210:211], v[18:19], v[242:243] neg_lo:[1,0,0] neg_hi:[1,0,0]
	v_pk_fma_f32 v[242:243], v[212:213], v[20:21], v[242:243] neg_lo:[1,0,0] neg_hi:[1,0,0]
	v_pk_fma_f32 v[242:243], v[214:215], v[22:23], v[242:243] neg_lo:[1,0,0] neg_hi:[1,0,0]
	v_pk_fma_f32 v[242:243], v[216:217], v[24:25], v[242:243] neg_lo:[1,0,0] neg_hi:[1,0,0]
	v_pk_fma_f32 v[242:243], v[218:219], v[26:27], v[242:243] neg_lo:[1,0,0] neg_hi:[1,0,0]
	v_pk_fma_f32 v[242:243], v[220:221], v[28:29], v[242:243] neg_lo:[1,0,0] neg_hi:[1,0,0]
	v_pk_fma_f32 v[242:243], v[222:223], v[30:31], v[242:243] neg_lo:[1,0,0] neg_hi:[1,0,0]
	v_cndmask_b32_e64 v240, 0, 1.0, vcc
	v_fma_f32 v242, -v224, v32, v242
	v_add_f32_e32 v33, v242, v243
	v_cmp_eq_u32_e32 vcc, 23, v95
	ds_read_b128 v[204:207], v11 offset:5888
	ds_read_b128 v[208:211], v11 offset:5904
	ds_read_b128 v[212:215], v11 offset:5920
	ds_read_b128 v[216:219], v11 offset:5936
	ds_read_b128 v[220:223], v11 offset:5952
	ds_read_b128 v[224:227], v11 offset:5968
	s_waitcnt lgkmcnt(6)
	v_pk_fma_f32 v[242:243], v[172:173], v[12:13], v[240:241] neg_lo:[1,0,0] neg_hi:[1,0,0]
	v_pk_fma_f32 v[242:243], v[174:175], v[14:15], v[242:243] neg_lo:[1,0,0] neg_hi:[1,0,0]
	v_pk_fma_f32 v[242:243], v[176:177], v[16:17], v[242:243] neg_lo:[1,0,0] neg_hi:[1,0,0]
	v_pk_fma_f32 v[242:243], v[178:179], v[18:19], v[242:243] neg_lo:[1,0,0] neg_hi:[1,0,0]
	v_pk_fma_f32 v[242:243], v[180:181], v[20:21], v[242:243] neg_lo:[1,0,0] neg_hi:[1,0,0]
	v_pk_fma_f32 v[242:243], v[182:183], v[22:23], v[242:243] neg_lo:[1,0,0] neg_hi:[1,0,0]
	v_pk_fma_f32 v[242:243], v[184:185], v[24:25], v[242:243] neg_lo:[1,0,0] neg_hi:[1,0,0]
	v_pk_fma_f32 v[242:243], v[186:187], v[26:27], v[242:243] neg_lo:[1,0,0] neg_hi:[1,0,0]
	v_pk_fma_f32 v[242:243], v[188:189], v[28:29], v[242:243] neg_lo:[1,0,0] neg_hi:[1,0,0]
	v_pk_fma_f32 v[242:243], v[190:191], v[30:31], v[242:243] neg_lo:[1,0,0] neg_hi:[1,0,0]
	v_pk_fma_f32 v[242:243], v[192:193], v[32:33], v[242:243] neg_lo:[1,0,0] neg_hi:[1,0,0]
	v_cndmask_b32_e64 v248, 0, 1.0, vcc
	v_add_f32_e32 v34, v242, v243
	v_cmp_eq_u32_e32 vcc, 24, v95
	ds_read_b128 v[172:175], v11 offset:6144
	ds_read_b128 v[176:179], v11 offset:6160
	ds_read_b128 v[180:183], v11 offset:6176
	ds_read_b128 v[184:187], v11 offset:6192
	ds_read_b128 v[188:191], v11 offset:6208
	ds_read_b128 v[192:195], v11 offset:6224
	s_waitcnt lgkmcnt(6)
	v_pk_fma_f32 v[242:243], v[204:205], v[12:13], v[248:249] neg_lo:[1,0,0] neg_hi:[1,0,0]
	v_pk_fma_f32 v[242:243], v[206:207], v[14:15], v[242:243] neg_lo:[1,0,0] neg_hi:[1,0,0]
	v_pk_fma_f32 v[242:243], v[208:209], v[16:17], v[242:243] neg_lo:[1,0,0] neg_hi:[1,0,0]
	v_pk_fma_f32 v[242:243], v[210:211], v[18:19], v[242:243] neg_lo:[1,0,0] neg_hi:[1,0,0]
	v_pk_fma_f32 v[242:243], v[212:213], v[20:21], v[242:243] neg_lo:[1,0,0] neg_hi:[1,0,0]
	v_pk_fma_f32 v[242:243], v[214:215], v[22:23], v[242:243] neg_lo:[1,0,0] neg_hi:[1,0,0]
	v_pk_fma_f32 v[242:243], v[216:217], v[24:25], v[242:243] neg_lo:[1,0,0] neg_hi:[1,0,0]
	v_pk_fma_f32 v[242:243], v[218:219], v[26:27], v[242:243] neg_lo:[1,0,0] neg_hi:[1,0,0]
	v_pk_fma_f32 v[242:243], v[220:221], v[28:29], v[242:243] neg_lo:[1,0,0] neg_hi:[1,0,0]
	v_pk_fma_f32 v[242:243], v[222:223], v[30:31], v[242:243] neg_lo:[1,0,0] neg_hi:[1,0,0]
	v_pk_fma_f32 v[242:243], v[224:225], v[32:33], v[242:243] neg_lo:[1,0,0] neg_hi:[1,0,0]
	v_cndmask_b32_e64 v240, 0, 1.0, vcc
	v_fma_f32 v242, -v226, v34, v242
	v_add_f32_e32 v35, v242, v243
	v_cmp_eq_u32_e32 vcc, 25, v95
	ds_read_b128 v[204:207], v11 offset:6400
	ds_read_b128 v[208:211], v11 offset:6416
	ds_read_b128 v[212:215], v11 offset:6432
	ds_read_b128 v[216:219], v11 offset:6448
	ds_read_b128 v[220:223], v11 offset:6464
	ds_read_b128 v[224:227], v11 offset:6480
	ds_read_b128 v[232:235], v11 offset:6496
	s_waitcnt lgkmcnt(7)
	v_pk_fma_f32 v[242:243], v[172:173], v[12:13], v[240:241] neg_lo:[1,0,0] neg_hi:[1,0,0]
	v_pk_fma_f32 v[242:243], v[174:175], v[14:15], v[242:243] neg_lo:[1,0,0] neg_hi:[1,0,0]
	v_pk_fma_f32 v[242:243], v[176:177], v[16:17], v[242:243] neg_lo:[1,0,0] neg_hi:[1,0,0]
	v_pk_fma_f32 v[242:243], v[178:179], v[18:19], v[242:243] neg_lo:[1,0,0] neg_hi:[1,0,0]
	v_pk_fma_f32 v[242:243], v[180:181], v[20:21], v[242:243] neg_lo:[1,0,0] neg_hi:[1,0,0]
	v_pk_fma_f32 v[242:243], v[182:183], v[22:23], v[242:243] neg_lo:[1,0,0] neg_hi:[1,0,0]
	v_pk_fma_f32 v[242:243], v[184:185], v[24:25], v[242:243] neg_lo:[1,0,0] neg_hi:[1,0,0]
	v_pk_fma_f32 v[242:243], v[186:187], v[26:27], v[242:243] neg_lo:[1,0,0] neg_hi:[1,0,0]
	v_pk_fma_f32 v[242:243], v[188:189], v[28:29], v[242:243] neg_lo:[1,0,0] neg_hi:[1,0,0]
	v_pk_fma_f32 v[242:243], v[190:191], v[30:31], v[242:243] neg_lo:[1,0,0] neg_hi:[1,0,0]
	v_pk_fma_f32 v[242:243], v[192:193], v[32:33], v[242:243] neg_lo:[1,0,0] neg_hi:[1,0,0]
	v_pk_fma_f32 v[242:243], v[194:195], v[34:35], v[242:243] neg_lo:[1,0,0] neg_hi:[1,0,0]
	v_cndmask_b32_e64 v248, 0, 1.0, vcc
	v_add_f32_e32 v36, v242, v243
	v_cmp_eq_u32_e32 vcc, 26, v95
	ds_read_b128 v[172:175], v11 offset:6656
	ds_read_b128 v[176:179], v11 offset:6672
	ds_read_b128 v[180:183], v11 offset:6688
	ds_read_b128 v[184:187], v11 offset:6704
	ds_read_b128 v[188:191], v11 offset:6720
	ds_read_b128 v[192:195], v11 offset:6736
	ds_read_b128 v[196:199], v11 offset:6752
	s_waitcnt lgkmcnt(7)
	v_pk_fma_f32 v[242:243], v[204:205], v[12:13], v[248:249] neg_lo:[1,0,0] neg_hi:[1,0,0]
	v_pk_fma_f32 v[242:243], v[206:207], v[14:15], v[242:243] neg_lo:[1,0,0] neg_hi:[1,0,0]
	v_pk_fma_f32 v[242:243], v[208:209], v[16:17], v[242:243] neg_lo:[1,0,0] neg_hi:[1,0,0]
	v_pk_fma_f32 v[242:243], v[210:211], v[18:19], v[242:243] neg_lo:[1,0,0] neg_hi:[1,0,0]
	v_pk_fma_f32 v[242:243], v[212:213], v[20:21], v[242:243] neg_lo:[1,0,0] neg_hi:[1,0,0]
	v_pk_fma_f32 v[242:243], v[214:215], v[22:23], v[242:243] neg_lo:[1,0,0] neg_hi:[1,0,0]
	v_pk_fma_f32 v[242:243], v[216:217], v[24:25], v[242:243] neg_lo:[1,0,0] neg_hi:[1,0,0]
	v_pk_fma_f32 v[242:243], v[218:219], v[26:27], v[242:243] neg_lo:[1,0,0] neg_hi:[1,0,0]
	v_pk_fma_f32 v[242:243], v[220:221], v[28:29], v[242:243] neg_lo:[1,0,0] neg_hi:[1,0,0]
	v_pk_fma_f32 v[242:243], v[222:223], v[30:31], v[242:243] neg_lo:[1,0,0] neg_hi:[1,0,0]
	v_pk_fma_f32 v[242:243], v[224:225], v[32:33], v[242:243] neg_lo:[1,0,0] neg_hi:[1,0,0]
	v_pk_fma_f32 v[242:243], v[226:227], v[34:35], v[242:243] neg_lo:[1,0,0] neg_hi:[1,0,0]
	v_cndmask_b32_e64 v240, 0, 1.0, vcc
	v_fma_f32 v242, -v232, v36, v242
	v_add_f32_e32 v37, v242, v243
	v_cmp_eq_u32_e32 vcc, 27, v95
	ds_read_b128 v[204:207], v11 offset:6912
	ds_read_b128 v[208:211], v11 offset:6928
	ds_read_b128 v[212:215], v11 offset:6944
	ds_read_b128 v[216:219], v11 offset:6960
	ds_read_b128 v[220:223], v11 offset:6976
	ds_read_b128 v[224:227], v11 offset:6992
	ds_read_b128 v[232:235], v11 offset:7008
	s_waitcnt lgkmcnt(7)
	v_pk_fma_f32 v[242:243], v[172:173], v[12:13], v[240:241] neg_lo:[1,0,0] neg_hi:[1,0,0]
	v_pk_fma_f32 v[242:243], v[174:175], v[14:15], v[242:243] neg_lo:[1,0,0] neg_hi:[1,0,0]
	v_pk_fma_f32 v[242:243], v[176:177], v[16:17], v[242:243] neg_lo:[1,0,0] neg_hi:[1,0,0]
	v_pk_fma_f32 v[242:243], v[178:179], v[18:19], v[242:243] neg_lo:[1,0,0] neg_hi:[1,0,0]
	v_pk_fma_f32 v[242:243], v[180:181], v[20:21], v[242:243] neg_lo:[1,0,0] neg_hi:[1,0,0]
	v_pk_fma_f32 v[242:243], v[182:183], v[22:23], v[242:243] neg_lo:[1,0,0] neg_hi:[1,0,0]
	v_pk_fma_f32 v[242:243], v[184:185], v[24:25], v[242:243] neg_lo:[1,0,0] neg_hi:[1,0,0]
	v_pk_fma_f32 v[242:243], v[186:187], v[26:27], v[242:243] neg_lo:[1,0,0] neg_hi:[1,0,0]
	v_pk_fma_f32 v[242:243], v[188:189], v[28:29], v[242:243] neg_lo:[1,0,0] neg_hi:[1,0,0]
	v_pk_fma_f32 v[242:243], v[190:191], v[30:31], v[242:243] neg_lo:[1,0,0] neg_hi:[1,0,0]
	v_pk_fma_f32 v[242:243], v[192:193], v[32:33], v[242:243] neg_lo:[1,0,0] neg_hi:[1,0,0]
	v_pk_fma_f32 v[242:243], v[194:195], v[34:35], v[242:243] neg_lo:[1,0,0] neg_hi:[1,0,0]
	v_pk_fma_f32 v[242:243], v[196:197], v[36:37], v[242:243] neg_lo:[1,0,0] neg_hi:[1,0,0]
	v_cndmask_b32_e64 v248, 0, 1.0, vcc
	v_add_f32_e32 v38, v242, v243
	v_cmp_eq_u32_e32 vcc, 28, v95
	ds_read_b128 v[172:175], v11 offset:7168
	ds_read_b128 v[176:179], v11 offset:7184
	ds_read_b128 v[180:183], v11 offset:7200
	ds_read_b128 v[184:187], v11 offset:7216
	ds_read_b128 v[188:191], v11 offset:7232
	ds_read_b128 v[192:195], v11 offset:7248
	ds_read_b128 v[196:199], v11 offset:7264
	s_waitcnt lgkmcnt(7)
	v_pk_fma_f32 v[242:243], v[204:205], v[12:13], v[248:249] neg_lo:[1,0,0] neg_hi:[1,0,0]
	v_pk_fma_f32 v[242:243], v[206:207], v[14:15], v[242:243] neg_lo:[1,0,0] neg_hi:[1,0,0]
	v_pk_fma_f32 v[242:243], v[208:209], v[16:17], v[242:243] neg_lo:[1,0,0] neg_hi:[1,0,0]
	v_pk_fma_f32 v[242:243], v[210:211], v[18:19], v[242:243] neg_lo:[1,0,0] neg_hi:[1,0,0]
	v_pk_fma_f32 v[242:243], v[212:213], v[20:21], v[242:243] neg_lo:[1,0,0] neg_hi:[1,0,0]
	v_pk_fma_f32 v[242:243], v[214:215], v[22:23], v[242:243] neg_lo:[1,0,0] neg_hi:[1,0,0]
	v_pk_fma_f32 v[242:243], v[216:217], v[24:25], v[242:243] neg_lo:[1,0,0] neg_hi:[1,0,0]
	v_pk_fma_f32 v[242:243], v[218:219], v[26:27], v[242:243] neg_lo:[1,0,0] neg_hi:[1,0,0]
	v_pk_fma_f32 v[242:243], v[220:221], v[28:29], v[242:243] neg_lo:[1,0,0] neg_hi:[1,0,0]
	v_pk_fma_f32 v[242:243], v[222:223], v[30:31], v[242:243] neg_lo:[1,0,0] neg_hi:[1,0,0]
	v_pk_fma_f32 v[242:243], v[224:225], v[32:33], v[242:243] neg_lo:[1,0,0] neg_hi:[1,0,0]
	v_pk_fma_f32 v[242:243], v[226:227], v[34:35], v[242:243] neg_lo:[1,0,0] neg_hi:[1,0,0]
	v_pk_fma_f32 v[242:243], v[232:233], v[36:37], v[242:243] neg_lo:[1,0,0] neg_hi:[1,0,0]
	v_cndmask_b32_e64 v240, 0, 1.0, vcc
	v_fma_f32 v242, -v234, v38, v242
	v_add_f32_e32 v39, v242, v243
	v_cmp_eq_u32_e32 vcc, 29, v95
	ds_read_b128 v[204:207], v11 offset:7424
	ds_read_b128 v[208:211], v11 offset:7440
	ds_read_b128 v[212:215], v11 offset:7456
	ds_read_b128 v[216:219], v11 offset:7472
	ds_read_b128 v[220:223], v11 offset:7488
	ds_read_b128 v[224:227], v11 offset:7504
	ds_read_b128 v[232:235], v11 offset:7520
	ds_read_b128 v[236:239], v11 offset:7536
	s_waitcnt lgkmcnt(8)
	v_pk_fma_f32 v[242:243], v[172:173], v[12:13], v[240:241] neg_lo:[1,0,0] neg_hi:[1,0,0]
	v_pk_fma_f32 v[242:243], v[174:175], v[14:15], v[242:243] neg_lo:[1,0,0] neg_hi:[1,0,0]
	v_pk_fma_f32 v[242:243], v[176:177], v[16:17], v[242:243] neg_lo:[1,0,0] neg_hi:[1,0,0]
	v_pk_fma_f32 v[242:243], v[178:179], v[18:19], v[242:243] neg_lo:[1,0,0] neg_hi:[1,0,0]
	v_pk_fma_f32 v[242:243], v[180:181], v[20:21], v[242:243] neg_lo:[1,0,0] neg_hi:[1,0,0]
	v_pk_fma_f32 v[242:243], v[182:183], v[22:23], v[242:243] neg_lo:[1,0,0] neg_hi:[1,0,0]
	v_pk_fma_f32 v[242:243], v[184:185], v[24:25], v[242:243] neg_lo:[1,0,0] neg_hi:[1,0,0]
	v_pk_fma_f32 v[242:243], v[186:187], v[26:27], v[242:243] neg_lo:[1,0,0] neg_hi:[1,0,0]
	v_pk_fma_f32 v[242:243], v[188:189], v[28:29], v[242:243] neg_lo:[1,0,0] neg_hi:[1,0,0]
	v_pk_fma_f32 v[242:243], v[190:191], v[30:31], v[242:243] neg_lo:[1,0,0] neg_hi:[1,0,0]
	v_pk_fma_f32 v[242:243], v[192:193], v[32:33], v[242:243] neg_lo:[1,0,0] neg_hi:[1,0,0]
	v_pk_fma_f32 v[242:243], v[194:195], v[34:35], v[242:243] neg_lo:[1,0,0] neg_hi:[1,0,0]
	v_pk_fma_f32 v[242:243], v[196:197], v[36:37], v[242:243] neg_lo:[1,0,0] neg_hi:[1,0,0]
	v_pk_fma_f32 v[242:243], v[198:199], v[38:39], v[242:243] neg_lo:[1,0,0] neg_hi:[1,0,0]
	v_cndmask_b32_e64 v248, 0, 1.0, vcc
	v_add_f32_e32 v40, v242, v243
	v_cmp_eq_u32_e32 vcc, 30, v95
	ds_read_b128 v[172:175], v11 offset:7680
	ds_read_b128 v[176:179], v11 offset:7696
	ds_read_b128 v[180:183], v11 offset:7712
	ds_read_b128 v[184:187], v11 offset:7728
	ds_read_b128 v[188:191], v11 offset:7744
	ds_read_b128 v[192:195], v11 offset:7760
	ds_read_b128 v[196:199], v11 offset:7776
	ds_read_b128 v[200:203], v11 offset:7792
	s_waitcnt lgkmcnt(8)
	v_pk_fma_f32 v[242:243], v[204:205], v[12:13], v[248:249] neg_lo:[1,0,0] neg_hi:[1,0,0]
	v_pk_fma_f32 v[242:243], v[206:207], v[14:15], v[242:243] neg_lo:[1,0,0] neg_hi:[1,0,0]
	v_pk_fma_f32 v[242:243], v[208:209], v[16:17], v[242:243] neg_lo:[1,0,0] neg_hi:[1,0,0]
	v_pk_fma_f32 v[242:243], v[210:211], v[18:19], v[242:243] neg_lo:[1,0,0] neg_hi:[1,0,0]
	v_pk_fma_f32 v[242:243], v[212:213], v[20:21], v[242:243] neg_lo:[1,0,0] neg_hi:[1,0,0]
	v_pk_fma_f32 v[242:243], v[214:215], v[22:23], v[242:243] neg_lo:[1,0,0] neg_hi:[1,0,0]
	v_pk_fma_f32 v[242:243], v[216:217], v[24:25], v[242:243] neg_lo:[1,0,0] neg_hi:[1,0,0]
	v_pk_fma_f32 v[242:243], v[218:219], v[26:27], v[242:243] neg_lo:[1,0,0] neg_hi:[1,0,0]
	v_pk_fma_f32 v[242:243], v[220:221], v[28:29], v[242:243] neg_lo:[1,0,0] neg_hi:[1,0,0]
	v_pk_fma_f32 v[242:243], v[222:223], v[30:31], v[242:243] neg_lo:[1,0,0] neg_hi:[1,0,0]
	v_pk_fma_f32 v[242:243], v[224:225], v[32:33], v[242:243] neg_lo:[1,0,0] neg_hi:[1,0,0]
	v_pk_fma_f32 v[242:243], v[226:227], v[34:35], v[242:243] neg_lo:[1,0,0] neg_hi:[1,0,0]
	v_pk_fma_f32 v[242:243], v[232:233], v[36:37], v[242:243] neg_lo:[1,0,0] neg_hi:[1,0,0]
	v_pk_fma_f32 v[242:243], v[234:235], v[38:39], v[242:243] neg_lo:[1,0,0] neg_hi:[1,0,0]
	v_cndmask_b32_e64 v240, 0, 1.0, vcc
	v_fma_f32 v242, -v236, v40, v242
	v_add_f32_e32 v41, v242, v243
	v_cmp_eq_u32_e32 vcc, 31, v95
	ds_read_b128 v[204:207], v11 offset:7936
	ds_read_b128 v[208:211], v11 offset:7952
	ds_read_b128 v[212:215], v11 offset:7968
	ds_read_b128 v[216:219], v11 offset:7984
	ds_read_b128 v[220:223], v11 offset:8000
	ds_read_b128 v[224:227], v11 offset:8016
	ds_read_b128 v[232:235], v11 offset:8032
	ds_read_b128 v[236:239], v11 offset:8048
	s_waitcnt lgkmcnt(8)
	v_pk_fma_f32 v[242:243], v[172:173], v[12:13], v[240:241] neg_lo:[1,0,0] neg_hi:[1,0,0]
	v_pk_fma_f32 v[242:243], v[174:175], v[14:15], v[242:243] neg_lo:[1,0,0] neg_hi:[1,0,0]
	v_pk_fma_f32 v[242:243], v[176:177], v[16:17], v[242:243] neg_lo:[1,0,0] neg_hi:[1,0,0]
	v_pk_fma_f32 v[242:243], v[178:179], v[18:19], v[242:243] neg_lo:[1,0,0] neg_hi:[1,0,0]
	v_pk_fma_f32 v[242:243], v[180:181], v[20:21], v[242:243] neg_lo:[1,0,0] neg_hi:[1,0,0]
	v_pk_fma_f32 v[242:243], v[182:183], v[22:23], v[242:243] neg_lo:[1,0,0] neg_hi:[1,0,0]
	v_pk_fma_f32 v[242:243], v[184:185], v[24:25], v[242:243] neg_lo:[1,0,0] neg_hi:[1,0,0]
	v_pk_fma_f32 v[242:243], v[186:187], v[26:27], v[242:243] neg_lo:[1,0,0] neg_hi:[1,0,0]
	v_pk_fma_f32 v[242:243], v[188:189], v[28:29], v[242:243] neg_lo:[1,0,0] neg_hi:[1,0,0]
	v_pk_fma_f32 v[242:243], v[190:191], v[30:31], v[242:243] neg_lo:[1,0,0] neg_hi:[1,0,0]
	v_pk_fma_f32 v[242:243], v[192:193], v[32:33], v[242:243] neg_lo:[1,0,0] neg_hi:[1,0,0]
	v_pk_fma_f32 v[242:243], v[194:195], v[34:35], v[242:243] neg_lo:[1,0,0] neg_hi:[1,0,0]
	v_pk_fma_f32 v[242:243], v[196:197], v[36:37], v[242:243] neg_lo:[1,0,0] neg_hi:[1,0,0]
	v_pk_fma_f32 v[242:243], v[198:199], v[38:39], v[242:243] neg_lo:[1,0,0] neg_hi:[1,0,0]
	v_pk_fma_f32 v[242:243], v[200:201], v[40:41], v[242:243] neg_lo:[1,0,0] neg_hi:[1,0,0]
	v_cndmask_b32_e64 v248, 0, 1.0, vcc
	v_add_f32_e32 v42, v242, v243
	s_waitcnt lgkmcnt(0)
	v_pk_fma_f32 v[242:243], v[204:205], v[12:13], v[248:249] neg_lo:[1,0,0] neg_hi:[1,0,0]
	v_pk_fma_f32 v[242:243], v[206:207], v[14:15], v[242:243] neg_lo:[1,0,0] neg_hi:[1,0,0]
	v_pk_fma_f32 v[242:243], v[208:209], v[16:17], v[242:243] neg_lo:[1,0,0] neg_hi:[1,0,0]
	v_pk_fma_f32 v[242:243], v[210:211], v[18:19], v[242:243] neg_lo:[1,0,0] neg_hi:[1,0,0]
	v_pk_fma_f32 v[242:243], v[212:213], v[20:21], v[242:243] neg_lo:[1,0,0] neg_hi:[1,0,0]
	v_pk_fma_f32 v[242:243], v[214:215], v[22:23], v[242:243] neg_lo:[1,0,0] neg_hi:[1,0,0]
	v_pk_fma_f32 v[242:243], v[216:217], v[24:25], v[242:243] neg_lo:[1,0,0] neg_hi:[1,0,0]
	v_pk_fma_f32 v[242:243], v[218:219], v[26:27], v[242:243] neg_lo:[1,0,0] neg_hi:[1,0,0]
	v_pk_fma_f32 v[242:243], v[220:221], v[28:29], v[242:243] neg_lo:[1,0,0] neg_hi:[1,0,0]
	v_pk_fma_f32 v[242:243], v[222:223], v[30:31], v[242:243] neg_lo:[1,0,0] neg_hi:[1,0,0]
	v_pk_fma_f32 v[242:243], v[224:225], v[32:33], v[242:243] neg_lo:[1,0,0] neg_hi:[1,0,0]
	v_pk_fma_f32 v[242:243], v[226:227], v[34:35], v[242:243] neg_lo:[1,0,0] neg_hi:[1,0,0]
	v_pk_fma_f32 v[242:243], v[232:233], v[36:37], v[242:243] neg_lo:[1,0,0] neg_hi:[1,0,0]
	v_pk_fma_f32 v[242:243], v[234:235], v[38:39], v[242:243] neg_lo:[1,0,0] neg_hi:[1,0,0]
	v_pk_fma_f32 v[242:243], v[236:237], v[40:41], v[242:243] neg_lo:[1,0,0] neg_hi:[1,0,0]
	v_fma_f32 v242, -v238, v42, v242
	v_add_f32_e32 v43, v242, v243
	v_cvt_pk_bf16_f32 v244, v12, v13
	ds_write_b16 v0, v244
	ds_write_b16_d16_hi v0, v244 offset:80
	v_cvt_pk_bf16_f32 v245, v14, v15
	ds_write_b16 v0, v245 offset:160
	ds_write_b16_d16_hi v0, v245 offset:240
	v_cvt_pk_bf16_f32 v244, v16, v17
	ds_write_b16 v0, v244 offset:320
	ds_write_b16_d16_hi v0, v244 offset:400
	v_cvt_pk_bf16_f32 v245, v18, v19
	ds_write_b16 v0, v245 offset:480
	ds_write_b16_d16_hi v0, v245 offset:560
	v_cvt_pk_bf16_f32 v244, v20, v21
	ds_write_b16 v0, v244 offset:640
	ds_write_b16_d16_hi v0, v244 offset:720
	v_cvt_pk_bf16_f32 v245, v22, v23
	ds_write_b16 v0, v245 offset:800
	ds_write_b16_d16_hi v0, v245 offset:880
	v_cvt_pk_bf16_f32 v244, v24, v25
	ds_write_b16 v0, v244 offset:960
	ds_write_b16_d16_hi v0, v244 offset:1040
	v_cvt_pk_bf16_f32 v245, v26, v27
	ds_write_b16 v0, v245 offset:1120
	ds_write_b16_d16_hi v0, v245 offset:1200
	v_cvt_pk_bf16_f32 v244, v28, v29
	ds_write_b16 v0, v244 offset:1280
	ds_write_b16_d16_hi v0, v244 offset:1360
	v_cvt_pk_bf16_f32 v245, v30, v31
	ds_write_b16 v0, v245 offset:1440
	ds_write_b16_d16_hi v0, v245 offset:1520
	v_cvt_pk_bf16_f32 v244, v32, v33
	ds_write_b16 v0, v244 offset:1600
	ds_write_b16_d16_hi v0, v244 offset:1680
	v_cvt_pk_bf16_f32 v245, v34, v35
	ds_write_b16 v0, v245 offset:1760
	ds_write_b16_d16_hi v0, v245 offset:1840
	v_cvt_pk_bf16_f32 v244, v36, v37
	ds_write_b16 v0, v244 offset:1920
	ds_write_b16_d16_hi v0, v244 offset:2000
	v_cvt_pk_bf16_f32 v245, v38, v39
	ds_write_b16 v0, v245 offset:2080
	ds_write_b16_d16_hi v0, v245 offset:2160
	v_cvt_pk_bf16_f32 v244, v40, v41
	ds_write_b16 v0, v244 offset:2240
	ds_write_b16_d16_hi v0, v244 offset:2320
	v_cvt_pk_bf16_f32 v245, v42, v43
	ds_write_b16 v0, v245 offset:2400
	ds_write_b16_d16_hi v0, v245 offset:2480
